# layer-0 in-projection phase no longer converts the 1024 deferred layer-1 weight items on its 3-unit workgroups; the 62 workgroups idle in layer 0's last up-projection round take them (on top of v14)
# speedup vs baseline: 1.0164x; 1.0016x over previous
.LBB0_295:
	s_cmpk_lt_i32 s64, 0x0
	s_cselect_b64 s[8:9], -1, 0
	s_and_b64 s[8:9], s[40:41], s[8:9]
	s_andn2_b64 vcc, exec, s[8:9]
	s_cbranch_vccnz .LBB0_391
	v_mov_b32_e32 v1, v224
	s_nop 0
	v_readfirstlane_b32 s8, v1
	s_ashr_i32 s54, s8, 6
	s_lshl_b32 s8, s64, 3
	s_add_i32 s8, s8, s54
	s_add_i32 s67, s8, 0x2340
	s_cmpk_gt_i32 s67, 0x273f
	s_cbranch_scc1 .LBB0_391
	s_mul_hi_i32 s8, s67, 0xae4c415d
	s_add_i32 s8, s8, s67
	s_load_dwordx4 s[12:15], s[36:37], 0x8
	s_load_dwordx4 s[16:19], s[36:37], 0x60
	s_load_dwordx2 s[10:11], s[36:37], 0x70
	s_load_dwordx2 s[42:43], s[36:37], 0x88
	s_lshr_b32 s9, s8, 31
	s_ashr_i32 s8, s8, 12
	s_add_i32 s50, s8, s9
	s_mul_i32 s8, s50, 0x1780
	s_sub_i32 s55, s67, s8
	s_ashr_i32 s51, s50, 31
	s_mul_i32 s9, s50, 0x1780000
	s_mul_hi_i32 s8, s50, 0x1780000
	s_add_u32 s46, s65, s9
	s_addc_u32 s47, s66, s8
	s_cmpk_gt_i32 s55, 0x4ff
	s_cbranch_scc0 .LBB0_302
	s_cmpk_gt_u32 s55, 0x6ff
	s_cbranch_scc0 .LBB0_303
	s_cmpk_gt_u32 s55, 0x11ff
	s_cbranch_scc0 .LBB0_708
	s_add_i32 s56, s55, 0xffffee00
	s_mul_i32 s8, s50, 0xb00000
	s_mul_hi_i32 s9, s50, 0xb00000
	s_waitcnt lgkmcnt(0)
	s_add_u32 s8, s42, s8
	s_addc_u32 s9, s43, s9
	s_add_u32 s44, s46, 0x1200000
	s_addc_u32 s45, s47, 0
	s_mov_b64 s[52:53], 0
	s_cbranch_execz .LBB0_709
	s_movk_i32 s68, 0xb00
	s_movk_i32 s27, 0x400
	s_mov_b32 s26, 0
	s_mov_b64 s[48:49], 0
	s_andn2_b64 vcc, exec, s[52:53]
	s_cbranch_vccz .LBB0_304
	s_branch .LBB0_305

.LBB0_892:
	s_mov_b32 s10, s2
	s_mov_b32 s11, s24
	s_cmpk_eq_i32 s11, 0x100
	s_cselect_b64 s[12:13], -1, 0
	s_cmpk_gt_i32 s10, 0xc1
	s_cselect_b64 s[14:15], -1, 0
	s_and_b64 s[12:13], s[12:13], s[14:15]
	s_andn2_b64 vcc, exec, s[12:13]
	s_cbranch_vccnz .LBB0_988
	v_mov_b32_e32 v1, v224
	s_lshl_b32 s10, s10, 3
	v_readfirstlane_b32 s11, v1
	s_ashr_i32 s50, s11, 6
	s_add_i32 s10, s10, s50
	s_add_i32 s60, s10, 0x1d30
	s_cmpk_gt_i32 s60, 0x2eff
	s_cbranch_scc1 .LBB0_988
	s_mul_hi_i32 s10, s60, 0xae4c415d
	s_add_i32 s10, s10, s60
	s_lshr_b32 s11, s10, 31
	s_ashr_i32 s10, s10, 12
	s_add_i32 s46, s10, s11
	s_load_dwordx4 s[12:15], s[38:39], 0x8
	s_load_dwordx4 s[16:19], s[38:39], 0x60
	s_load_dwordx2 s[40:41], s[38:39], 0x70
	s_nop 0
	s_load_dwordx2 s[38:39], s[38:39], 0x88
	s_mul_i32 s10, s46, 0x1780
	s_sub_i32 s51, s60, s10
	s_add_u32 s61, s36, 0x100000
	s_addc_u32 s62, s37, 0
	s_ashr_i32 s47, s46, 31
	s_mul_i32 s11, s46, 0x1780000
	s_mul_hi_i32 s10, s46, 0x1780000
	s_add_u32 s42, s61, s11
	s_addc_u32 s43, s62, s10
	s_cmpk_gt_i32 s51, 0x4ff
	s_cbranch_scc0 .LBB0_899
	s_cmpk_gt_u32 s51, 0x6ff
	s_cbranch_scc0 .LBB0_900
	s_cmpk_gt_u32 s51, 0x11ff
	s_cbranch_scc0 .LBB0_1578
	s_add_i32 s52, s51, 0xffffee00
	s_mul_i32 s10, s46, 0xb00000
	s_mul_hi_i32 s11, s46, 0xb00000
	s_waitcnt lgkmcnt(0)
	s_add_u32 s10, s38, s10
	s_addc_u32 s11, s39, s11
	s_add_u32 s36, s42, 0x1200000
	s_addc_u32 s37, s43, 0
	s_mov_b64 s[48:49], 0
	s_cbranch_execz .LBB0_1579
	s_movk_i32 s63, 0xb00
	s_movk_i32 s27, 0x400
	s_mov_b32 s26, 0
	s_mov_b64 s[44:45], 0
	s_andn2_b64 vcc, exec, s[48:49]
	s_cbranch_vccz .LBB0_901
	s_branch .LBB0_902
